# GLA-output item: early touch of the second 128-byte line of the gate-residual row (warm-up load before the first two residual loads)
# speedup vs baseline: 1.0097x; 1.0097x over previous
; DI f32x4 mfma16(bf16x8 a, bf16x8 b, f32x4 c) { return __builtin_amdgcn_mfma_f32_16x16x32_bf16(a, b, c, 0, 0, 0); }
; DI void go_compute(int l, const unsigned char* base, const bf16x8 (&qq)[4], int item, int tb, int lane) {
;     unsigned char* R = WSP() + WS_R;
;     const bf16* GR = (const bf16*)(R + R_GR); bf16* MIX = (bf16*)(R + R_MIX);
;     const int ck = item & 63, bh = item >> 6, h = bh & 3, b = bh >> 2, c = lane & 15, g = lane >> 4;
;     const size_t tok0 = (size_t)b * SEQ + ck * 64;
;     const bf16x8 qf0 = qq[0], qf1 = qq[1], qb0 = qq[2], qb1 = qq[3];
;     f32x4 at[4];
; #pragma unroll
;     for (int sb = 0; sb < 4; ++sb) {
;         const unsigned char* kf = base + GO_KF + (16 * sb + c) * 144 + g * 16; const unsigned char* kb = base + GO_KB + (16 * sb + c) * 144 + g * 16;
;         f32x4 f = {0.f, 0.f, 0.f, 0.f}, bk = {0.f, 0.f, 0.f, 0.f};
;         f = mfma16(*(const bf16x8*)kf, qf0, f); f = mfma16(*(const bf16x8*)(kf + 64), qf1, f);
;         bk = mfma16(*(const bf16x8*)kb, qb0, bk); bk = mfma16(*(const bf16x8*)(kb + 64), qb1, bk);
; #pragma unroll
;         for (int i = 0; i < 4; ++i) at[sb][i] = (16 * sb + 4 * g + i <= 16 * tb + c) ? f[i] : bk[i];
;     }
;     const bf16x8 p0 = pack8(at[0], at[1]), p1 = pack8(at[2], at[3]);
;     f32x4 o[8]; float ss = 0.f;
; #pragma unroll
;     for (int eb = 0; eb < 8; ++eb) {
;         const unsigned char* vp = base + GO_VT + (g >> 1) * 2048 + (16 * eb + c) * 16 + (g & 1) * 8;
;         const u32x2 v0 = *(const u32x2*)vp, v1 = *(const u32x2*)(vp + 4096), v2 = *(const u32x2*)(vp + 8192), v3 = *(const u32x2*)(vp + 12288);
;         u32x4 a0; a0.x = v0.x; a0.y = v0.y; a0.z = v1.x; a0.w = v1.y; u32x4 a1; a1.x = v2.x; a1.y = v2.y; a1.z = v3.x; a1.w = v3.y;
;         const unsigned char* sfp = base + GO_SF + (16 * eb + c) * 144 + g * 16; const unsigned char* sbp = base + GO_SB + (16 * eb + c) * 144 + g * 16;
;         f32x4 acc = {0.f, 0.f, 0.f, 0.f};
;         acc = mfma16(__builtin_bit_cast(bf16x8, a0), p0, acc); acc = mfma16(__builtin_bit_cast(bf16x8, a1), p1, acc);
;         acc = mfma16(*(const bf16x8*)sfp, qf0, acc); acc = mfma16(*(const bf16x8*)(sfp + 64), qf1, acc);
;         acc = mfma16(*(const bf16x8*)sbp, qb0, acc); acc = mfma16(*(const bf16x8*)(sbp + 64), qb1, acc);
;         o[eb] = acc; ss += (acc[0] * acc[0] + acc[1] * acc[1]) + (acc[2] * acc[2] + acc[3] * acc[3]);
;     }
.LBB0_873:
	v_readlane_b32 s8, v244, 9
	s_add_i32 s8, s8, s31
	v_readlane_b32 s12, v246, 63
	s_or_b32 s8, s8, s12
	s_movk_i32 s12, 0xa8
	ds_read_b128 v[98:101], v161
	ds_read_b128 v[102:105], v161 offset:64
	s_ashr_i32 s13, s12, 31
	s_add_u32 s12, s0, s12
	s_addc_u32 s13, s1, s13
	s_load_dwordx2 s[40:41], s[12:13], 0x0
	s_waitcnt lgkmcnt(0)
	v_mfma_f32_16x16x32_bf16 v[98:101], v[98:101], v[94:97], 0
	ds_read_b128 v[106:109], v161 offset:9280
	s_ashr_i32 s12, s8, 8
	s_ashr_i32 s13, s12, 31
	v_mfma_f32_16x16x32_bf16 v[98:101], v[102:105], v[90:93], v[98:101]
	ds_read_b128 v[102:105], v161 offset:9216
	s_and_b32 s8, s30, 0xfc0
	s_lshl_b64 s[12:13], s[12:13], 12
	s_or_b32 s8, s12, s8
	s_movk_i32 s12, 0x68
	s_waitcnt lgkmcnt(0)
	v_mfma_f32_16x16x32_bf16 v[102:105], v[102:105], v[86:89], 0
	v_mfma_f32_16x16x32_bf16 v[102:105], v[106:109], v[82:85], v[102:105]
	ds_read_b128 v[106:109], v161 offset:11584
	s_nop 6
	v_cndmask_b32_e64 v0, v98, v102, s[42:43]
	v_cndmask_b32_e64 v110, v103, v99, s[44:45]
	v_cndmask_b32_e64 v111, v100, v104, s[46:47]
	v_cndmask_b32_e64 v112, v101, v105, s[48:49]
	ds_read_b128 v[98:101], v161 offset:2304
	ds_read_b128 v[102:105], v161 offset:2368
	s_waitcnt lgkmcnt(1)
	v_mfma_f32_16x16x32_bf16 v[98:101], v[98:101], v[94:97], 0
	v_cvt_pk_bf16_f32 v114, v0, v110
	v_add_u32_e32 v0, v145, v147
	v_cvt_pk_bf16_f32 v115, v111, v112
	s_waitcnt lgkmcnt(0)
	v_mfma_f32_16x16x32_bf16 v[98:101], v[102:105], v[90:93], v[98:101]
	ds_read_b128 v[102:105], v161 offset:11520
	s_waitcnt lgkmcnt(0)
	v_mfma_f32_16x16x32_bf16 v[102:105], v[102:105], v[86:89], 0
	v_mfma_f32_16x16x32_bf16 v[102:105], v[106:109], v[82:85], v[102:105]
	ds_read_b128 v[106:109], v161 offset:13888
	s_nop 6
	v_cndmask_b32_e64 v113, v98, v102, s[50:51]
	v_cndmask_b32_e64 v116, v99, v103, s[52:53]
	v_cndmask_b32_e64 v117, v100, v104, s[54:55]
	v_cndmask_b32_e64 v118, v101, v105, s[56:57]
	ds_read_b128 v[98:101], v161 offset:4608
	ds_read_b128 v[102:105], v161 offset:4672
	s_waitcnt lgkmcnt(1)
	v_mfma_f32_16x16x32_bf16 v[98:101], v[98:101], v[94:97], 0
	v_cvt_pk_bf16_f32 v117, v117, v118
	v_cvt_pk_bf16_f32 v116, v113, v116
	s_waitcnt lgkmcnt(0)
	v_mfma_f32_16x16x32_bf16 v[98:101], v[102:105], v[90:93], v[98:101]
	ds_read_b128 v[102:105], v161 offset:13824
	s_waitcnt lgkmcnt(0)
	v_mfma_f32_16x16x32_bf16 v[102:105], v[102:105], v[86:89], 0
	v_mfma_f32_16x16x32_bf16 v[102:105], v[106:109], v[82:85], v[102:105]
	ds_read_b128 v[106:109], v162 offset:9280
	s_nop 6
	v_cndmask_b32_e64 v119, v98, v102, s[58:59]
	v_cndmask_b32_e64 v120, v99, v103, s[60:61]
	v_cndmask_b32_e64 v121, v100, v104, s[62:63]
	v_cndmask_b32_e64 v122, v101, v105, s[64:65]
	ds_read_b128 v[98:101], v162
	ds_read_b128 v[102:105], v162 offset:64
	s_waitcnt lgkmcnt(1)
	v_mfma_f32_16x16x32_bf16 v[98:101], v[98:101], v[94:97], 0
	v_cvt_pk_bf16_f32 v118, v119, v120
	v_cvt_pk_bf16_f32 v119, v121, v122
	s_waitcnt lgkmcnt(0)
	v_mfma_f32_16x16x32_bf16 v[98:101], v[102:105], v[90:93], v[98:101]
	ds_read_b128 v[102:105], v162 offset:9216
	s_waitcnt lgkmcnt(0)
	v_mfma_f32_16x16x32_bf16 v[102:105], v[102:105], v[86:89], 0
	v_mfma_f32_16x16x32_bf16 v[102:105], v[106:109], v[82:85], v[102:105]
	s_nop 7
	v_cndmask_b32_e64 v98, v98, v102, s[66:67]
	v_cndmask_b32_e64 v99, v99, v103, s[68:69]
	v_cndmask_b32_e64 v100, v100, v104, s[70:71]
	v_cndmask_b32_e64 v101, v101, v105, s[72:73]
	v_cvt_pk_bf16_f32 v120, v98, v99
	v_cvt_pk_bf16_f32 v121, v100, v101
	ds_read2st64_b64 v[208:211], v0 offset0:36 offset1:44
	ds_read2st64_b64 v[212:215], v0 offset0:52 offset1:60
	ds_read_b128 v[216:219], v161 offset:34816
	ds_read_b128 v[220:223], v161 offset:34880
	ds_read_b128 v[224:227], v161 offset:53248
	ds_read_b128 v[228:231], v161 offset:53312
	s_waitcnt lgkmcnt(5)
	v_mfma_f32_16x16x32_bf16 v[98:101], v[208:211], v[114:117], 0
	ds_read2st64_b64 v[232:235], v163 offset0:36 offset1:44
	s_waitcnt lgkmcnt(5)
	v_mfma_f32_16x16x32_bf16 v[98:101], v[212:215], v[118:121], v[98:101]
	ds_read2st64_b64 v[208:211], v163 offset0:52 offset1:60
	s_waitcnt lgkmcnt(5)
	v_mfma_f32_16x16x32_bf16 v[98:101], v[216:219], v[94:97], v[98:101]
	ds_read_b128 v[212:215], v161 offset:37120
	s_waitcnt lgkmcnt(5)
	v_mfma_f32_16x16x32_bf16 v[98:101], v[220:223], v[90:93], v[98:101]
	ds_read_b128 v[216:219], v161 offset:37184
	s_waitcnt lgkmcnt(5)
	v_mfma_f32_16x16x32_bf16 v[98:101], v[224:227], v[86:89], v[98:101]
	ds_read_b128 v[220:223], v161 offset:55552
	s_waitcnt lgkmcnt(5)
	v_mfma_f32_16x16x32_bf16 v[98:101], v[228:231], v[82:85], v[98:101]
	ds_read_b128 v[224:227], v161 offset:55616
	s_waitcnt lgkmcnt(5)
	v_mfma_f32_16x16x32_bf16 v[102:105], v[232:235], v[114:117], 0
	ds_read2st64_b64 v[228:231], v178 offset0:36 offset1:44
	s_waitcnt lgkmcnt(5)
	v_mfma_f32_16x16x32_bf16 v[102:105], v[208:211], v[118:121], v[102:105]
	ds_read2st64_b64 v[232:235], v178 offset0:52 offset1:60
	s_waitcnt lgkmcnt(5)
	v_mfma_f32_16x16x32_bf16 v[102:105], v[212:215], v[94:97], v[102:105]
	ds_read_b128 v[208:211], v161 offset:39424
	v_mul_f32_e32 v240, v99, v99
	v_mul_f32_e32 v241, v101, v101
	v_fmac_f32_e32 v240, v98, v98
	v_fmac_f32_e32 v241, v100, v100
	v_add_f32_e32 v240, v240, v241
	v_mov_b32_e32 v242, v240
	s_waitcnt lgkmcnt(5)
	v_mfma_f32_16x16x32_bf16 v[102:105], v[216:219], v[90:93], v[102:105]
	ds_read_b128 v[212:215], v161 offset:39488
	s_waitcnt lgkmcnt(5)
	v_mfma_f32_16x16x32_bf16 v[102:105], v[220:223], v[86:89], v[102:105]
	ds_read_b128 v[216:219], v161 offset:57856
	s_waitcnt lgkmcnt(5)
	v_mfma_f32_16x16x32_bf16 v[102:105], v[224:227], v[82:85], v[102:105]
	ds_read_b128 v[220:223], v161 offset:57920
	s_waitcnt lgkmcnt(5)
; DI f32x4 mfma16(bf16x8 a, bf16x8 b, f32x4 c) { return __builtin_amdgcn_mfma_f32_16x16x32_bf16(a, b, c, 0, 0, 0); }
; DI void go_compute(int l, const unsigned char* base, const bf16x8 (&qq)[4], int item, int tb, int lane) {
;     ...
; #pragma unroll
;     for (int eb = 0; eb < 8; ++eb) {
;         const unsigned char* vp = base + GO_VT + (g >> 1) * 2048 + (16 * eb + c) * 16 + (g & 1) * 8;
;         const u32x2 v0 = *(const u32x2*)vp, v1 = *(const u32x2*)(vp + 4096), v2 = *(const u32x2*)(vp + 8192), v3 = *(const u32x2*)(vp + 12288);
;         u32x4 a0; a0.x = v0.x; a0.y = v0.y; a0.z = v1.x; a0.w = v1.y; u32x4 a1; a1.x = v2.x; a1.y = v2.y; a1.z = v3.x; a1.w = v3.y;
;         const unsigned char* sfp = base + GO_SF + (16 * eb + c) * 144 + g * 16; const unsigned char* sbp = base + GO_SB + (16 * eb + c) * 144 + g * 16;
;         f32x4 acc = {0.f, 0.f, 0.f, 0.f};
;         acc = mfma16(__builtin_bit_cast(bf16x8, a0), p0, acc); acc = mfma16(__builtin_bit_cast(bf16x8, a1), p1, acc);
;         acc = mfma16(*(const bf16x8*)sfp, qf0, acc); acc = mfma16(*(const bf16x8*)(sfp + 64), qf1, acc);
;         acc = mfma16(*(const bf16x8*)sbp, qb0, acc); acc = mfma16(*(const bf16x8*)(sbp + 64), qb1, acc);
;         o[eb] = acc; ss += (acc[0] * acc[0] + acc[1] * acc[1]) + (acc[2] * acc[2] + acc[3] * acc[3]);
;     }
	v_mfma_f32_16x16x32_bf16 v[106:109], v[228:231], v[114:117], 0
	ds_read2st64_b64 v[224:227], v179 offset0:36 offset1:44
	s_waitcnt lgkmcnt(5)
	v_mfma_f32_16x16x32_bf16 v[106:109], v[232:235], v[118:121], v[106:109]
	ds_read2st64_b64 v[228:231], v179 offset0:52 offset1:60
	s_waitcnt lgkmcnt(5)
	v_mfma_f32_16x16x32_bf16 v[106:109], v[208:211], v[94:97], v[106:109]
	ds_read_b128 v[232:235], v162 offset:34816
	v_mul_f32_e32 v240, v103, v103
	v_mul_f32_e32 v241, v105, v105
	v_fmac_f32_e32 v240, v102, v102
	v_fmac_f32_e32 v241, v104, v104
	v_add_f32_e32 v240, v240, v241
	v_add_f32_e32 v242, v242, v240
	s_waitcnt lgkmcnt(5)
	v_mfma_f32_16x16x32_bf16 v[106:109], v[212:215], v[90:93], v[106:109]
	ds_read_b128 v[208:211], v162 offset:34880
	s_waitcnt lgkmcnt(5)
	v_mfma_f32_16x16x32_bf16 v[106:109], v[216:219], v[86:89], v[106:109]
	ds_read_b128 v[212:215], v162 offset:53248
	s_waitcnt lgkmcnt(5)
	v_mfma_f32_16x16x32_bf16 v[106:109], v[220:223], v[82:85], v[106:109]
	ds_read_b128 v[216:219], v162 offset:53312
	s_waitcnt lgkmcnt(5)
	v_mfma_f32_16x16x32_bf16 v[110:113], v[224:227], v[114:117], 0
	ds_read2st64_b64 v[220:223], v180 offset0:36 offset1:44
	s_waitcnt lgkmcnt(5)
	v_mfma_f32_16x16x32_bf16 v[110:113], v[228:231], v[118:121], v[110:113]
	ds_read2st64_b64 v[224:227], v180 offset0:52 offset1:60
	s_waitcnt lgkmcnt(5)
	v_mfma_f32_16x16x32_bf16 v[110:113], v[232:235], v[94:97], v[110:113]
	ds_read_b128 v[228:231], v181 offset:34816
	v_mul_f32_e32 v240, v107, v107
	v_mul_f32_e32 v241, v109, v109
	v_fmac_f32_e32 v240, v106, v106
	v_fmac_f32_e32 v241, v108, v108
	v_add_f32_e32 v240, v240, v241
	v_add_f32_e32 v242, v242, v240
	s_waitcnt lgkmcnt(5)
	v_mfma_f32_16x16x32_bf16 v[110:113], v[208:211], v[90:93], v[110:113]
	ds_read_b128 v[232:235], v181 offset:34880
	s_waitcnt lgkmcnt(5)
	v_mfma_f32_16x16x32_bf16 v[110:113], v[212:215], v[86:89], v[110:113]
	ds_read_b128 v[208:211], v181 offset:53248
	s_waitcnt lgkmcnt(5)
	v_mfma_f32_16x16x32_bf16 v[110:113], v[216:219], v[82:85], v[110:113]
	ds_read_b128 v[212:215], v181 offset:53312
	s_waitcnt lgkmcnt(5)
	v_mfma_f32_16x16x32_bf16 v[122:125], v[220:223], v[114:117], 0
	ds_read2st64_b64 v[216:219], v182 offset0:36 offset1:44
	s_waitcnt lgkmcnt(5)
	v_mfma_f32_16x16x32_bf16 v[122:125], v[224:227], v[118:121], v[122:125]
	ds_read2st64_b64 v[220:223], v182 offset0:52 offset1:60
	s_waitcnt lgkmcnt(5)
	v_mfma_f32_16x16x32_bf16 v[122:125], v[228:231], v[94:97], v[122:125]
	ds_read_b128 v[224:227], v181 offset:37120
	v_mul_f32_e32 v240, v111, v111
	v_mul_f32_e32 v241, v113, v113
	v_fmac_f32_e32 v240, v110, v110
	v_fmac_f32_e32 v241, v112, v112
	v_add_f32_e32 v240, v240, v241
	v_add_f32_e32 v242, v242, v240
	s_waitcnt lgkmcnt(5)
	v_mfma_f32_16x16x32_bf16 v[122:125], v[232:235], v[90:93], v[122:125]
	ds_read_b128 v[228:231], v181 offset:37184
	s_waitcnt lgkmcnt(5)
	v_mfma_f32_16x16x32_bf16 v[122:125], v[208:211], v[86:89], v[122:125]
	ds_read_b128 v[232:235], v181 offset:55552
	s_waitcnt lgkmcnt(5)
	v_mfma_f32_16x16x32_bf16 v[122:125], v[212:215], v[82:85], v[122:125]
	ds_read_b128 v[208:211], v181 offset:55616
	s_waitcnt lgkmcnt(5)
	v_mfma_f32_16x16x32_bf16 v[126:129], v[216:219], v[114:117], 0
	ds_read2st64_b64 v[212:215], v183 offset0:36 offset1:44
	s_waitcnt lgkmcnt(5)
	v_mfma_f32_16x16x32_bf16 v[126:129], v[220:223], v[118:121], v[126:129]
	ds_read2st64_b64 v[216:219], v183 offset0:52 offset1:60
	s_waitcnt lgkmcnt(5)
	v_mfma_f32_16x16x32_bf16 v[126:129], v[224:227], v[94:97], v[126:129]
	ds_read_b128 v[220:223], v181 offset:39424
	v_mul_f32_e32 v240, v123, v123
	v_mul_f32_e32 v241, v125, v125
	v_fmac_f32_e32 v240, v122, v122
	v_fmac_f32_e32 v241, v124, v124
	v_add_f32_e32 v240, v240, v241
	v_add_f32_e32 v242, v242, v240
	s_waitcnt lgkmcnt(5)
	v_mfma_f32_16x16x32_bf16 v[126:129], v[228:231], v[90:93], v[126:129]
	ds_read_b128 v[224:227], v181 offset:39488
	s_waitcnt lgkmcnt(5)
	v_mfma_f32_16x16x32_bf16 v[126:129], v[232:235], v[86:89], v[126:129]
	ds_read_b128 v[228:231], v181 offset:57856
	s_waitcnt lgkmcnt(5)
	v_mfma_f32_16x16x32_bf16 v[126:129], v[208:211], v[82:85], v[126:129]
	ds_read_b128 v[232:235], v181 offset:57920
	s_waitcnt lgkmcnt(5)
	v_mfma_f32_16x16x32_bf16 v[130:133], v[212:215], v[114:117], 0
	ds_read2st64_b64 v[208:211], v184 offset0:36 offset1:44
	s_waitcnt lgkmcnt(5)
	v_mfma_f32_16x16x32_bf16 v[130:133], v[216:219], v[118:121], v[130:133]
	ds_read2st64_b64 v[212:215], v184 offset0:52 offset1:60
	s_waitcnt lgkmcnt(5)
	v_mfma_f32_16x16x32_bf16 v[130:133], v[220:223], v[94:97], v[130:133]
	ds_read_b128 v[216:219], v185 offset:34816
	v_mul_f32_e32 v240, v127, v127
	v_mul_f32_e32 v241, v129, v129
	v_fmac_f32_e32 v240, v126, v126
	v_fmac_f32_e32 v241, v128, v128
	v_add_f32_e32 v240, v240, v241
	v_add_f32_e32 v242, v242, v240
	s_waitcnt lgkmcnt(5)
	v_mfma_f32_16x16x32_bf16 v[130:133], v[224:227], v[90:93], v[130:133]
	ds_read_b128 v[220:223], v185 offset:34880
	s_waitcnt lgkmcnt(5)
	v_mfma_f32_16x16x32_bf16 v[130:133], v[228:231], v[86:89], v[130:133]
	ds_read_b128 v[224:227], v185 offset:53248
	s_waitcnt lgkmcnt(5)
	v_mfma_f32_16x16x32_bf16 v[130:133], v[232:235], v[82:85], v[130:133]
	ds_read_b128 v[228:231], v185 offset:53312
	s_waitcnt lgkmcnt(5)
	v_mfma_f32_16x16x32_bf16 v[236:239], v[208:211], v[114:117], 0
	s_waitcnt lgkmcnt(4)
	v_mfma_f32_16x16x32_bf16 v[236:239], v[212:215], v[118:121], v[236:239]
	s_waitcnt lgkmcnt(3)
	v_mfma_f32_16x16x32_bf16 v[236:239], v[216:219], v[94:97], v[236:239]
	v_mul_f32_e32 v240, v131, v131
	v_mul_f32_e32 v241, v133, v133
	v_fmac_f32_e32 v240, v130, v130
	v_fmac_f32_e32 v241, v132, v132
	v_add_f32_e32 v240, v240, v241
	v_add_f32_e32 v242, v242, v240
	s_waitcnt lgkmcnt(2)
; DI unsigned pk2(float lo, float hi) { return pg8::cvt_pk_bf16(lo, hi); }
; DI float bflo(unsigned w) { return __uint_as_float(w << 16); }
; DI float bfhi(unsigned w) { return __uint_as_float(w & 0xffff0000u); }
; DI float silu_f(float x) { return x * __builtin_amdgcn_rcpf(1.0f + __expf(-x)); }
; #define INP(i) ((const float*)karg(8 * (i)))
; DI void go_compute(int l, const unsigned char* base, const bf16x8 (&qq)[4], int item, int tb, int lane) {
;     ...
;         o[eb] = acc; ss += (acc[0] * acc[0] + acc[1] * acc[1]) + (acc[2] * acc[2] + acc[3] * acc[3]);
;     }
;     ss += __shfl_xor(ss, 16); ss += __shfl_xor(ss, 32);
;     const float rstd = rsqrtf(ss * (1.0f / 128.0f) + EPS);
;     const float* gain = INP(13) + l * 128 + 4 * g;
;     const size_t tok = tok0 + 16 * tb + c;
; #pragma unroll
;     for (int eb = 0; eb < 8; ++eb) {
;         const f32x4 gn = *(const f32x4*)(gain + 16 * eb);
;         const u32x2 gr = *(const u32x2*)(GR + tok * 512 + h * 128 + 16 * eb + 4 * g);
;         const float r0 = bflo(gr.x), r1 = bfhi(gr.x), r2 = bflo(gr.y), r3 = bfhi(gr.y);
;         u32x2 w; w.x = pk2(o[eb][0] * rstd * gn[0] * silu_f(r0), o[eb][1] * rstd * gn[1] * silu_f(r1)); w.y = pk2(o[eb][2] * rstd * gn[2] * silu_f(r2), o[eb][3] * rstd * gn[3] * silu_f(r3));
;         *(u32x2*)(MIX + tok * 1024 + 512 + h * 128 + 16 * eb + 4 * g) = w;
;     }
	v_mfma_f32_16x16x32_bf16 v[236:239], v[220:223], v[90:93], v[236:239]
	s_waitcnt lgkmcnt(1)
	v_mfma_f32_16x16x32_bf16 v[236:239], v[224:227], v[86:89], v[236:239]
	s_waitcnt lgkmcnt(0)
	v_mfma_f32_16x16x32_bf16 v[82:85], v[228:231], v[82:85], v[236:239]
	s_nop 7
	v_mul_f32_e32 v240, v83, v83
	v_mul_f32_e32 v241, v85, v85
	v_fmac_f32_e32 v240, v82, v82
	v_fmac_f32_e32 v241, v84, v84
	v_add_f32_e32 v240, v240, v241
	v_add_f32_e32 v242, v242, v240
	s_ashr_i32 s15, s12, 31
	s_add_u32 s14, s0, s12
	s_addc_u32 s15, s1, s15
	s_load_dwordx2 s[14:15], s[14:15], 0x0
	v_lshlrev_b32_e32 v91, 2, v152
	v_mov_b32_e32 v116, v242
	s_waitcnt lgkmcnt(0)
	s_add_u32 s14, s14, s2
	s_addc_u32 s15, s15, s3
	global_load_dwordx4 v[208:211], v91, s[14:15]
	global_load_dwordx4 v[212:215], v91, s[14:15] offset:64
	global_load_dwordx4 v[216:219], v91, s[14:15] offset:128
	global_load_dwordx4 v[220:223], v91, s[14:15] offset:192
	global_load_dwordx4 v[224:227], v91, s[14:15] offset:256
	global_load_dwordx4 v[228:231], v91, s[14:15] offset:320
	global_load_dwordx4 v[232:235], v91, s[14:15] offset:384
	global_load_dwordx4 v[236:239], v91, s[14:15] offset:448
	v_mov_b32_e32 v87, s13
	v_or_b32_e32 v86, s8, v148
	v_lshlrev_b64 v[88:89], 10, v[86:87]
	s_and_b32 s8, s29, 0x180
	v_lshl_add_u64 v[88:89], s[40:41], 0, v[88:89]
	s_lshl_b32 s8, s8, 1
	v_lshlrev_b64 v[86:87], 11, v[86:87]
	v_lshl_add_u64 v[88:89], v[88:89], 0, s[8:9]
	v_lshlrev_b32_e32 v0, 1, v152
	v_lshl_add_u64 v[86:87], s[40:41], 0, v[86:87]
	v_lshl_add_u64 v[96:97], v[88:89], 0, v[0:1]
	v_lshl_add_u64 v[86:87], v[86:87], 0, s[8:9]
	s_mov_b64 s[12:13], 0x11600000
	s_mov_b32 s8, 0x11600000
	v_lshl_add_u64 v[94:95], v[96:97], 0, s[12:13]
	v_add_co_u32_e32 v96, vcc, s8, v96
	v_lshl_add_u64 v[114:115], v[86:87], 0, v[0:1]
	s_nop 0
	v_addc_co_u32_e32 v97, vcc, 0, v97, vcc
	global_load_dword v117, v[94:95], off offset:128
	global_load_dwordx2 v[240:241], v[94:95], off
	global_load_dwordx2 v[242:243], v[94:95], off offset:32
	v_and_b32_e32 v87, 64, v194
	v_xor_b32_e32 v86, 16, v194
	v_add_u32_e32 v87, 64, v87
	v_cmp_lt_i32_e32 vcc, v86, v87
	s_nop 1
	v_cndmask_b32_e32 v86, v194, v86, vcc
	v_lshlrev_b32_e32 v86, 2, v86
	ds_bpermute_b32 v86, v86, v116
	s_waitcnt lgkmcnt(0)
	v_add_f32_e32 v116, v116, v86
	v_xor_b32_e32 v86, 32, v194
	v_cmp_lt_i32_e32 vcc, v86, v87
	s_nop 1
	v_cndmask_b32_e32 v86, v194, v86, vcc
	v_lshlrev_b32_e32 v86, 2, v86
	ds_bpermute_b32 v86, v86, v116
	s_waitcnt lgkmcnt(0)
	v_add_f32_e32 v116, v116, v86
	v_fmamk_f32 v116, v116, 0x3c000000, v164
	v_cmp_gt_f32_e32 vcc, s25, v116
	v_mul_f32_e32 v86, 0x4b800000, v116
	s_nop 0
	v_cndmask_b32_e32 v116, v116, v86, vcc
	v_rsq_f32_e32 v116, v116
	s_nop 0
	v_mul_f32_e32 v86, 0x45800000, v116
	v_cndmask_b32_e32 v90, v116, v86, vcc
	v_pk_mul_f32 v[98:99], v[98:99], v[90:91] op_sel_hi:[1,0]
	v_pk_mul_f32 v[100:101], v[100:101], v[90:91] op_sel_hi:[1,0]
	s_mov_b32 s8, 0x1b600000
	v_pk_mul_f32 v[102:103], v[102:103], v[90:91] op_sel_hi:[1,0]
	s_mov_b64 s[12:13], 0x1b600400
	v_lshl_add_u64 v[92:93], v[114:115], 0, s[12:13]
	v_pk_mul_f32 v[82:83], v[82:83], v[90:91] op_sel_hi:[1,0]
	v_pk_mul_f32 v[84:85], v[84:85], v[90:91] op_sel_hi:[1,0]
	s_waitcnt vmcnt(1)
	s_nop 1
	v_mov_b32_e32 v86, v208
	v_mov_b32_e32 v87, v209
	v_mov_b32_e32 v88, v210
	v_mov_b32_e32 v89, v211
	v_mov_b32_e32 v96, v240
	v_mov_b32_e32 v97, v241
	global_load_dwordx2 v[240:241], v[94:95], off offset:64
	v_lshlrev_b32_e32 v116, 16, v96
	v_mul_f32_e32 v0, 0xbfb8aa3b, v116
	v_exp_f32_e32 v0, v0
	v_and_b32_e32 v117, 0xffff0000, v96
	v_lshlrev_b32_e32 v96, 16, v97
	v_pk_mul_f32 v[86:87], v[86:87], v[98:99]
	v_add_f32_e32 v0, 1.0, v0
	v_rcp_f32_e32 v118, v0
	v_mul_f32_e32 v0, 0xbfb8aa3b, v117
	v_exp_f32_e32 v0, v0
	v_and_b32_e32 v97, 0xffff0000, v97
	v_pk_mul_f32 v[88:89], v[88:89], v[100:101]
	v_add_f32_e32 v0, 1.0, v0
	v_rcp_f32_e32 v119, v0
	v_mul_f32_e32 v0, 0xbfb8aa3b, v96
	v_exp_f32_e32 v0, v0
	v_pk_mul_f32 v[98:99], v[118:119], v[116:117]
	s_nop 0
	v_pk_mul_f32 v[86:87], v[86:87], v[98:99]
	v_add_f32_e32 v0, 1.0, v0
	v_rcp_f32_e32 v98, v0
	v_mul_f32_e32 v0, 0xbfb8aa3b, v97
	v_exp_f32_e32 v0, v0
	v_cvt_pk_bf16_f32 v86, v86, v87
	v_add_f32_e32 v0, 1.0, v0
	v_rcp_f32_e32 v99, v0
	s_nop 0
	v_pk_mul_f32 v[96:97], v[98:99], v[96:97]
	s_nop 0
	v_pk_mul_f32 v[88:89], v[88:89], v[96:97]
	s_nop 0
	v_cvt_pk_bf16_f32 v87, v88, v89
	v_add_co_u32_e32 v88, vcc, s8, v114
	v_readlane_b32 s8, v244, 5
	s_nop 0
	v_addc_co_u32_e32 v89, vcc, 0, v115, vcc
	global_store_dwordx2 v[88:89], v[86:87], off offset:1024
	s_nop 0
	s_add_i32 s29, s29, s8
	v_readlane_b32 s8, v244, 8
	s_add_i32 s30, s30, s8
	v_readlane_b32 s8, v244, 10
	s_add_i32 s31, s31, s8
	s_andn2_b64 vcc, exec, s[38:39]
	s_waitcnt vmcnt(2)
	s_nop 1
	v_mov_b32_e32 v86, v212
	v_mov_b32_e32 v87, v213
	v_mov_b32_e32 v88, v214
	v_mov_b32_e32 v89, v215
	v_mov_b32_e32 v96, v242
	v_mov_b32_e32 v97, v243
	global_load_dwordx2 v[242:243], v[94:95], off offset:96
	v_pk_mul_f32 v[86:87], v[86:87], v[102:103]
	v_lshlrev_b32_e32 v98, 16, v96
	v_mul_f32_e32 v0, 0xbfb8aa3b, v98
	v_exp_f32_e32 v0, v0
	v_and_b32_e32 v99, 0xffff0000, v96
	v_lshlrev_b32_e32 v96, 16, v97
	v_and_b32_e32 v97, 0xffff0000, v97
	v_add_f32_e32 v0, 1.0, v0
	v_rcp_f32_e32 v100, v0
	v_mul_f32_e32 v0, 0xbfb8aa3b, v99
	v_exp_f32_e32 v0, v0
	v_pk_mul_f32 v[102:103], v[106:107], v[90:91] op_sel_hi:[1,0]
	v_add_f32_e32 v0, 1.0, v0
	v_rcp_f32_e32 v101, v0
	v_mul_f32_e32 v0, 0xbfb8aa3b, v96
	v_exp_f32_e32 v0, v0
	v_pk_mul_f32 v[98:99], v[100:101], v[98:99]
	s_nop 0
	v_pk_mul_f32 v[86:87], v[86:87], v[98:99]
	v_add_f32_e32 v0, 1.0, v0
	v_rcp_f32_e32 v98, v0
	v_mul_f32_e32 v0, 0xbfb8aa3b, v97
	v_exp_f32_e32 v0, v0
	v_pk_mul_f32 v[100:101], v[104:105], v[90:91] op_sel_hi:[1,0]
	v_cvt_pk_bf16_f32 v86, v86, v87
	v_pk_mul_f32 v[88:89], v[88:89], v[100:101]
	v_add_f32_e32 v0, 1.0, v0
	v_rcp_f32_e32 v99, v0
	s_nop 0
	v_pk_mul_f32 v[96:97], v[98:99], v[96:97]
	s_nop 0
	v_pk_mul_f32 v[88:89], v[88:89], v[96:97]
	s_nop 0
	v_cvt_pk_bf16_f32 v87, v88, v89
	global_store_dwordx2 v[92:93], v[86:87], off offset:32
	s_nop 0
	s_waitcnt vmcnt(3)
; DI unsigned pk2(float lo, float hi) { return pg8::cvt_pk_bf16(lo, hi); }
; DI float bflo(unsigned w) { return __uint_as_float(w << 16); }
; DI float bfhi(unsigned w) { return __uint_as_float(w & 0xffff0000u); }
; DI float silu_f(float x) { return x * __builtin_amdgcn_rcpf(1.0f + __expf(-x)); }
; DI void go_compute(int l, const unsigned char* base, const bf16x8 (&qq)[4], int item, int tb, int lane) {
;     ...
;     for (int eb = 0; eb < 8; ++eb) {
;         const f32x4 gn = *(const f32x4*)(gain + 16 * eb);
;         const u32x2 gr = *(const u32x2*)(GR + tok * 512 + h * 128 + 16 * eb + 4 * g);
;         const float r0 = bflo(gr.x), r1 = bfhi(gr.x), r2 = bflo(gr.y), r3 = bfhi(gr.y);
;         u32x2 w; w.x = pk2(o[eb][0] * rstd * gn[0] * silu_f(r0), o[eb][1] * rstd * gn[1] * silu_f(r1)); w.y = pk2(o[eb][2] * rstd * gn[2] * silu_f(r2), o[eb][3] * rstd * gn[3] * silu_f(r3));
;         *(u32x2*)(MIX + tok * 1024 + 512 + h * 128 + 16 * eb + 4 * g) = w;
	s_nop 1
	v_mov_b32_e32 v86, v216
	v_mov_b32_e32 v87, v217
	v_mov_b32_e32 v88, v218
	v_mov_b32_e32 v89, v219
	v_mov_b32_e32 v96, v240
	v_mov_b32_e32 v97, v241
	global_load_dwordx2 v[240:241], v[94:95], off offset:128
	v_pk_mul_f32 v[86:87], v[86:87], v[102:103]
	v_lshlrev_b32_e32 v98, 16, v96
	v_mul_f32_e32 v0, 0xbfb8aa3b, v98
	v_exp_f32_e32 v0, v0
	v_and_b32_e32 v99, 0xffff0000, v96
	v_lshlrev_b32_e32 v96, 16, v97
	v_and_b32_e32 v97, 0xffff0000, v97
	v_add_f32_e32 v0, 1.0, v0
	v_rcp_f32_e32 v100, v0
	v_mul_f32_e32 v0, 0xbfb8aa3b, v99
	v_exp_f32_e32 v0, v0
	v_pk_mul_f32 v[102:103], v[110:111], v[90:91] op_sel_hi:[1,0]
	v_add_f32_e32 v0, 1.0, v0
	v_rcp_f32_e32 v101, v0
	v_mul_f32_e32 v0, 0xbfb8aa3b, v96
	v_exp_f32_e32 v0, v0
	v_pk_mul_f32 v[98:99], v[100:101], v[98:99]
	s_nop 0
	v_pk_mul_f32 v[86:87], v[86:87], v[98:99]
	v_add_f32_e32 v0, 1.0, v0
	v_rcp_f32_e32 v98, v0
	v_mul_f32_e32 v0, 0xbfb8aa3b, v97
	v_exp_f32_e32 v0, v0
	v_pk_mul_f32 v[100:101], v[108:109], v[90:91] op_sel_hi:[1,0]
	v_cvt_pk_bf16_f32 v86, v86, v87
	v_pk_mul_f32 v[88:89], v[88:89], v[100:101]
	v_add_f32_e32 v0, 1.0, v0
	v_rcp_f32_e32 v99, v0
	s_nop 0
	v_pk_mul_f32 v[96:97], v[98:99], v[96:97]
	s_nop 0
	v_pk_mul_f32 v[88:89], v[88:89], v[96:97]
	s_nop 0
	v_cvt_pk_bf16_f32 v87, v88, v89
	global_store_dwordx2 v[92:93], v[86:87], off offset:64
	s_nop 0
	s_waitcnt vmcnt(3)
	s_nop 1
	v_mov_b32_e32 v86, v220
	v_mov_b32_e32 v87, v221
	v_mov_b32_e32 v88, v222
	v_mov_b32_e32 v89, v223
	v_mov_b32_e32 v96, v242
	v_mov_b32_e32 v97, v243
	global_load_dwordx2 v[242:243], v[94:95], off offset:160
	v_pk_mul_f32 v[86:87], v[102:103], v[86:87]
	v_lshlrev_b32_e32 v98, 16, v96
	v_mul_f32_e32 v0, 0xbfb8aa3b, v98
	v_exp_f32_e32 v0, v0
	v_and_b32_e32 v99, 0xffff0000, v96
	v_lshlrev_b32_e32 v96, 16, v97
	v_and_b32_e32 v97, 0xffff0000, v97
	v_add_f32_e32 v0, 1.0, v0
	v_rcp_f32_e32 v100, v0
	v_mul_f32_e32 v0, 0xbfb8aa3b, v99
	v_exp_f32_e32 v0, v0
	v_pk_mul_f32 v[102:103], v[122:123], v[90:91] op_sel_hi:[1,0]
	v_add_f32_e32 v0, 1.0, v0
	v_rcp_f32_e32 v101, v0
	v_mul_f32_e32 v0, 0xbfb8aa3b, v96
	v_exp_f32_e32 v0, v0
	v_pk_mul_f32 v[98:99], v[100:101], v[98:99]
	s_nop 0
	v_pk_mul_f32 v[86:87], v[86:87], v[98:99]
	v_add_f32_e32 v0, 1.0, v0
	v_rcp_f32_e32 v98, v0
	v_mul_f32_e32 v0, 0xbfb8aa3b, v97
	v_exp_f32_e32 v0, v0
	v_pk_mul_f32 v[100:101], v[112:113], v[90:91] op_sel_hi:[1,0]
	v_cvt_pk_bf16_f32 v86, v86, v87
	v_pk_mul_f32 v[88:89], v[100:101], v[88:89]
	v_add_f32_e32 v0, 1.0, v0
	v_rcp_f32_e32 v99, v0
	s_nop 0
	v_pk_mul_f32 v[96:97], v[98:99], v[96:97]
	s_nop 0
	v_pk_mul_f32 v[88:89], v[88:89], v[96:97]
	s_nop 0
	v_cvt_pk_bf16_f32 v87, v88, v89
	global_store_dwordx2 v[92:93], v[86:87], off offset:96
	s_nop 0
	s_waitcnt vmcnt(3)
	s_nop 1
	v_mov_b32_e32 v86, v224
	v_mov_b32_e32 v87, v225
	v_mov_b32_e32 v88, v226
	v_mov_b32_e32 v89, v227
	v_mov_b32_e32 v96, v240
	v_mov_b32_e32 v97, v241
	global_load_dwordx2 v[240:241], v[94:95], off offset:192
	v_pk_mul_f32 v[86:87], v[102:103], v[86:87]
	v_lshlrev_b32_e32 v98, 16, v96
	v_mul_f32_e32 v0, 0xbfb8aa3b, v98
	v_exp_f32_e32 v0, v0
	v_and_b32_e32 v99, 0xffff0000, v96
	v_lshlrev_b32_e32 v96, 16, v97
	v_and_b32_e32 v97, 0xffff0000, v97
	v_add_f32_e32 v0, 1.0, v0
	v_rcp_f32_e32 v100, v0
	v_mul_f32_e32 v0, 0xbfb8aa3b, v99
	v_exp_f32_e32 v0, v0
	v_pk_mul_f32 v[102:103], v[126:127], v[90:91] op_sel_hi:[1,0]
	v_add_f32_e32 v0, 1.0, v0
	v_rcp_f32_e32 v101, v0
	v_mul_f32_e32 v0, 0xbfb8aa3b, v96
	v_exp_f32_e32 v0, v0
	v_pk_mul_f32 v[98:99], v[100:101], v[98:99]
	s_nop 0
	v_pk_mul_f32 v[86:87], v[86:87], v[98:99]
	v_add_f32_e32 v0, 1.0, v0
	v_rcp_f32_e32 v98, v0
	v_mul_f32_e32 v0, 0xbfb8aa3b, v97
	v_exp_f32_e32 v0, v0
	v_pk_mul_f32 v[100:101], v[124:125], v[90:91] op_sel_hi:[1,0]
	v_cvt_pk_bf16_f32 v86, v86, v87
	v_pk_mul_f32 v[88:89], v[100:101], v[88:89]
	v_add_f32_e32 v0, 1.0, v0
	v_rcp_f32_e32 v99, v0
	s_nop 0
	v_pk_mul_f32 v[96:97], v[98:99], v[96:97]
	s_nop 0
	v_pk_mul_f32 v[88:89], v[88:89], v[96:97]
	s_nop 0
	v_cvt_pk_bf16_f32 v87, v88, v89
	global_store_dwordx2 v[92:93], v[86:87], off offset:128
	s_nop 0
	s_waitcnt vmcnt(3)
; DI unsigned pk2(float lo, float hi) { return pg8::cvt_pk_bf16(lo, hi); }
; DI float bflo(unsigned w) { return __uint_as_float(w << 16); }
; DI float bfhi(unsigned w) { return __uint_as_float(w & 0xffff0000u); }
; DI float silu_f(float x) { return x * __builtin_amdgcn_rcpf(1.0f + __expf(-x)); }
; #define SCHED_FENCE() __builtin_amdgcn_sched_barrier(0)
; DI void go_compute(int l, const unsigned char* base, const bf16x8 (&qq)[4], int item, int tb, int lane) {
;     ...
;     for (int eb = 0; eb < 8; ++eb) {
;         const f32x4 gn = *(const f32x4*)(gain + 16 * eb);
;         const u32x2 gr = *(const u32x2*)(GR + tok * 512 + h * 128 + 16 * eb + 4 * g);
;         const float r0 = bflo(gr.x), r1 = bfhi(gr.x), r2 = bflo(gr.y), r3 = bfhi(gr.y);
;         u32x2 w; w.x = pk2(o[eb][0] * rstd * gn[0] * silu_f(r0), o[eb][1] * rstd * gn[1] * silu_f(r1)); w.y = pk2(o[eb][2] * rstd * gn[2] * silu_f(r2), o[eb][3] * rstd * gn[3] * silu_f(r3));
;         *(u32x2*)(MIX + tok * 1024 + 512 + h * 128 + 16 * eb + 4 * g) = w;
;     }
; DI void gla_out_phase(int l, unsigned char* ldsb, int tid, int wave, int lane, bool xl, int xq, int k0, int kend, int kstep) {
;     ...
;         go_lwrite(st, base, t256);
;         bf16x8 qq[4] = {st.q[0], st.q[1], st.q[2], st.q[3]};
;         __syncthreads();
;         if (k + kstep < kend) go_gload(st, go_item(xl, xq, k + kstep, half), t256, tb, lane);
;         SCHED_FENCE();
;         go_compute(l, base, qq, go_item(xl, xq, k, half), tb, lane);
;         __syncthreads();
	s_nop 1
	v_mov_b32_e32 v86, v228
	v_mov_b32_e32 v87, v229
	v_mov_b32_e32 v88, v230
	v_mov_b32_e32 v89, v231
	v_mov_b32_e32 v96, v242
	v_mov_b32_e32 v97, v243
	global_load_dwordx2 v[242:243], v[94:95], off offset:224
	v_pk_mul_f32 v[86:87], v[102:103], v[86:87]
	v_lshlrev_b32_e32 v98, 16, v96
	v_mul_f32_e32 v0, 0xbfb8aa3b, v98
	v_exp_f32_e32 v0, v0
	v_and_b32_e32 v99, 0xffff0000, v96
	v_lshlrev_b32_e32 v96, 16, v97
	v_and_b32_e32 v97, 0xffff0000, v97
	v_add_f32_e32 v0, 1.0, v0
	v_rcp_f32_e32 v100, v0
	v_mul_f32_e32 v0, 0xbfb8aa3b, v99
	v_exp_f32_e32 v0, v0
	v_pk_mul_f32 v[102:103], v[130:131], v[90:91] op_sel_hi:[1,0]
	v_add_f32_e32 v0, 1.0, v0
	v_rcp_f32_e32 v101, v0
	v_mul_f32_e32 v0, 0xbfb8aa3b, v96
	v_exp_f32_e32 v0, v0
	v_pk_mul_f32 v[98:99], v[100:101], v[98:99]
	s_nop 0
	v_pk_mul_f32 v[86:87], v[86:87], v[98:99]
	v_add_f32_e32 v0, 1.0, v0
	v_rcp_f32_e32 v98, v0
	v_mul_f32_e32 v0, 0xbfb8aa3b, v97
	v_exp_f32_e32 v0, v0
	v_pk_mul_f32 v[100:101], v[128:129], v[90:91] op_sel_hi:[1,0]
	v_cvt_pk_bf16_f32 v86, v86, v87
	v_pk_mul_f32 v[88:89], v[100:101], v[88:89]
	v_add_f32_e32 v0, 1.0, v0
	v_rcp_f32_e32 v99, v0
	s_nop 0
	v_pk_mul_f32 v[96:97], v[98:99], v[96:97]
	s_nop 0
	v_pk_mul_f32 v[88:89], v[88:89], v[96:97]
	s_nop 0
	v_cvt_pk_bf16_f32 v87, v88, v89
	global_store_dwordx2 v[92:93], v[86:87], off offset:160
	s_nop 0
	s_waitcnt vmcnt(3)
	s_nop 1
	v_mov_b32_e32 v86, v232
	v_mov_b32_e32 v87, v233
	v_mov_b32_e32 v88, v234
	v_mov_b32_e32 v89, v235
	v_mov_b32_e32 v96, v240
	v_mov_b32_e32 v97, v241
	v_pk_mul_f32 v[86:87], v[102:103], v[86:87]
	v_lshlrev_b32_e32 v98, 16, v96
	v_mul_f32_e32 v0, 0xbfb8aa3b, v98
	v_exp_f32_e32 v0, v0
	v_and_b32_e32 v99, 0xffff0000, v96
	v_lshlrev_b32_e32 v96, 16, v97
	v_and_b32_e32 v97, 0xffff0000, v97
	v_add_f32_e32 v0, 1.0, v0
	v_rcp_f32_e32 v100, v0
	v_mul_f32_e32 v0, 0xbfb8aa3b, v99
	v_exp_f32_e32 v0, v0
	s_nop 0
	v_add_f32_e32 v0, 1.0, v0
	v_rcp_f32_e32 v101, v0
	v_mul_f32_e32 v0, 0xbfb8aa3b, v96
	v_exp_f32_e32 v0, v0
	v_pk_mul_f32 v[98:99], v[100:101], v[98:99]
	s_nop 0
	v_pk_mul_f32 v[86:87], v[86:87], v[98:99]
	v_add_f32_e32 v0, 1.0, v0
	v_rcp_f32_e32 v98, v0
	v_mul_f32_e32 v0, 0xbfb8aa3b, v97
	v_exp_f32_e32 v0, v0
	v_pk_mul_f32 v[100:101], v[132:133], v[90:91] op_sel_hi:[1,0]
	v_cvt_pk_bf16_f32 v86, v86, v87
	v_pk_mul_f32 v[88:89], v[100:101], v[88:89]
	v_add_f32_e32 v0, 1.0, v0
	v_rcp_f32_e32 v99, v0
	s_nop 0
	v_pk_mul_f32 v[96:97], v[98:99], v[96:97]
	s_nop 0
	v_pk_mul_f32 v[88:89], v[88:89], v[96:97]
	s_nop 0
	v_cvt_pk_bf16_f32 v87, v88, v89
	global_store_dwordx2 v[92:93], v[86:87], off offset:192
	s_nop 0
	s_waitcnt vmcnt(2)
	s_nop 1
	v_mov_b32_e32 v86, v236
	v_mov_b32_e32 v87, v237
	v_mov_b32_e32 v88, v238
	v_mov_b32_e32 v89, v239
	v_mov_b32_e32 v94, v242
	v_mov_b32_e32 v95, v243
	v_pk_mul_f32 v[82:83], v[82:83], v[86:87]
	v_lshlrev_b32_e32 v96, 16, v94
	v_mul_f32_e32 v0, 0xbfb8aa3b, v96
	v_exp_f32_e32 v0, v0
	v_and_b32_e32 v97, 0xffff0000, v94
	v_pk_mul_f32 v[84:85], v[84:85], v[88:89]
	v_add_f32_e32 v0, 1.0, v0
	v_rcp_f32_e32 v98, v0
	v_mul_f32_e32 v0, 0xbfb8aa3b, v97
	v_exp_f32_e32 v0, v0
	s_nop 0
	v_add_f32_e32 v0, 1.0, v0
	v_rcp_f32_e32 v99, v0
	s_nop 0
	v_pk_mul_f32 v[86:87], v[98:99], v[96:97]
	s_nop 0
	v_pk_mul_f32 v[82:83], v[82:83], v[86:87]
	v_lshlrev_b32_e32 v86, 16, v95
	v_mul_f32_e32 v0, 0xbfb8aa3b, v86
	v_exp_f32_e32 v0, v0
	v_and_b32_e32 v87, 0xffff0000, v95
	v_cvt_pk_bf16_f32 v82, v82, v83
	v_add_f32_e32 v0, 1.0, v0
	v_rcp_f32_e32 v94, v0
	v_mul_f32_e32 v0, 0xbfb8aa3b, v87
	v_exp_f32_e32 v0, v0
	s_nop 0
	v_add_f32_e32 v0, 1.0, v0
	v_rcp_f32_e32 v95, v0
	s_nop 0
	v_pk_mul_f32 v[86:87], v[94:95], v[86:87]
	s_nop 0
	v_pk_mul_f32 v[84:85], v[84:85], v[86:87]
	v_mov_b64_e32 v[88:89], v[76:77]
	v_cvt_pk_bf16_f32 v83, v84, v85
	global_store_dwordx2 v[92:93], v[82:83], off offset:224
	v_mov_b64_e32 v[84:85], v[80:81]
	v_mov_b64_e32 v[92:93], v[72:73]
	v_mov_b64_e32 v[96:97], v[68:69]
	v_mov_b64_e32 v[82:83], v[78:79]
	v_mov_b64_e32 v[86:87], v[74:75]
	v_mov_b64_e32 v[90:91], v[70:71]
	v_mov_b64_e32 v[94:95], v[66:67]
	s_barrier
	s_cbranch_vccz .LBB0_876
